# P2y load balance variant: GLA sample iterations 3/3/2/0 for blockIdx&3 = 0/1/2/3
# baseline (speedup 1.0000x reference)
.Lp2y_samp:
	s_add_i32 s100, s100, 1
	s_and_b32 s0, s101, 3
	s_cmp_eq_u32 s100, 1
	s_cbranch_scc0 .Lp2y_s2
	s_add_i32 s50, s101, 0x100
	s_branch .LBB0_704
.Lp2y_s2:
	s_cmp_eq_u32 s100, 2
	s_cbranch_scc0 .LBB0_854
	s_cmp_eq_u32 s0, 2
	s_cbranch_scc1 .LBB0_854
	s_cmp_eq_u32 s0, 0
	s_cselect_b32 s1, 3, 0x102
	s_add_i32 s50, s101, s1
	s_branch .LBB0_704
